# v032 + grid barrier one release hop fewer + moba_select q slices via LDS broadcast + GEMM K-loop saddr-form requests and loop-edge rotation
# speedup vs baseline: 1.0053x; 1.0005x over previous
; __device__ __forceinline__ int lane_now() { int l; asm volatile("v_mbcnt_lo_u32_b32 %0, -1, 0\n\tv_mbcnt_hi_u32_b32 %0, -1, %0" : "=v"(l)); return l; }
; #define WSL(F) ws_opaque((F).ws)
; #define WAVE(F) int_opaque((F).wave)
; #define VCU(F) int_opaque((F).vcu)
; __device__ __forceinline__ void moba_select_phase(Frame& F) {
;     const int lane = lane_now();
;     const int wv_ = WAVE(F), gw = VCU(F) * NWAVES + wv_, NGW = F.G * NWAVES, n = lane >> 2, part = lane & 3;
;     const bf16* PROJ = (const bf16*)(WSL(F) + WS_PROJ); const float* KMEAN = (const float*)(WSL(F) + WS_KMEAN); unsigned* MMASK = (unsigned*)(WSL(F) + WS_MMASK);
;     for (int m4 = gw; m4 < M / 4; m4 += NGW) {
;         const int m0 = m4 * 4, b = m0 / T, own = (m0 % T) >> 8;
;         f32x4 kmA[8], kmB[8]; v4u qA[4][4], qB[4][4];
.LBB0_264:
	s_cmp_le_i32 s52, s31
	v_readlane_b32 s18, v255, 19
	s_cselect_b64 s[14:15], -1, 0
	s_mul_i32 s18, s18, 10
	s_and_b64 s[14:15], s[14:15], s[26:27]
	s_add_i32 s20, s18, 4
	s_cmp_lt_i32 s20, s53
	s_cselect_b64 s[44:45], -1, 0
	s_and_b64 vcc, exec, s[14:15]
	v_readlane_b32 s19, v255, 20
	s_cbranch_vccz .LBB0_613
	v_readlane_b32 s14, v253, 3
	v_readlane_b32 s15, v253, 2
	v_writelane_b32 v255, s44, 41
	v_mbcnt_lo_u32_b32 v2, -1, 0
	v_mbcnt_hi_u32_b32 v2, -1, v2
	s_lshl_b32 s18, s15, 3
	s_add_i32 s18, s18, s14
	v_writelane_b32 v255, s45, 42
	v_writelane_b32 v255, s20, 43
	s_mov_b64 s[26:27], s[96:97]
	s_mov_b64 s[50:51], s[96:97]
	s_mov_b64 s[52:53], s[96:97]
	s_cmpk_gt_i32 s18, 0x7ff
	s_mov_b64 s[78:79], 0x2400
	s_cbranch_scc1 .LBB0_336
	v_lshlrev_b32_e32 v0, 5, v2
	v_and_b32_e32 v4, 0x60, v0
	s_add_u32 s19, s26, 0x3c900000
	v_lshlrev_b32_e32 v0, 2, v4
	s_addc_u32 s20, s27, 0
	v_lshl_add_u64 v[6:7], s[50:51], 0, v[0:1]
	s_mov_b64 s[28:29], 0x72600000
	s_lshl_b32 s15, s15, 5
	s_lshl_b32 s14, s14, 2
	v_ashrrev_i32_e32 v212, 2, v2
	v_lshrrev_b32_e32 v224, 4, v2
	v_mul_u32_u24_e32 v224, 0x6000, v224
	v_and_b32_e32 v225, 15, v2
	v_lshl_add_u32 v224, v225, 4, v224
	v_readlane_b32 s32, v253, 3
	s_lshl_b32 s32, s32, 10
	v_and_b32_e32 v226, 3, v2
	v_lshl_add_u32 v225, v2, 4, s32
	v_lshl_add_u32 v226, v226, 6, s32
	v_lshl_add_u64 v[162:163], v[6:7], 0, s[28:29]
	v_and_b32_e32 v0, 3, v2
	s_add_i32 s28, s15, s14
	v_cmp_eq_u32_e64 s[40:41], 0, v2
	v_lshlrev_b32_e32 v164, 6, v0
	v_mov_b32_e32 v165, v1
	s_or_b32 s29, s28, 3
	s_or_b32 s31, s28, 2
	s_or_b32 s34, s28, 1
	v_lshlrev_b32_e32 v166, 7, v0
	v_mov_b32_e32 v167, v1
	v_add_u32_e32 v213, 16, v212
	v_lshlrev_b32_e32 v0, 1, v4
	s_branch .LBB0_268

; __device__ __forceinline__ void moba_select_phase(Frame& F) {
;     ...
;         MS_LOAD(kmA, qA, 0);
.LBB0_284:
	s_or_b64 exec, exec, s[14:15]
	s_mul_i32 s98, s35, 0x6000
	s_mul_hi_i32 s99, s35, 0x6000
	s_add_u32 s98, s19, s98
	s_addc_u32 s99, s20, s99
	s_add_u32 s98, s98, 0x2400
	s_addc_u32 s99, s99, 0
	s_mul_i32 s15, s29, 0x6000
	s_mul_hi_i32 s14, s29, 0x6000
	s_add_u32 s54, s26, s15
	s_addc_u32 s55, s27, s14
	s_mul_i32 s15, s31, 0x6000
	s_mul_hi_i32 s14, s31, 0x6000
	s_add_u32 s56, s26, s15
	s_addc_u32 s57, s27, s14
	s_mul_i32 s15, s34, 0x6000
	s_mul_hi_i32 s14, s34, 0x6000
	s_add_u32 s58, s26, s15
	s_addc_u32 s59, s27, s14
	s_mul_i32 s15, s28, 0x6000
	s_mul_hi_i32 s14, s28, 0x6000
	s_add_u32 s60, s26, s15
	s_addc_u32 s61, s27, s14
	s_mul_i32 s14, s35, 0x6000
	s_mul_hi_i32 s15, s35, 0x6000
	s_add_u32 s14, s19, s14
	s_addc_u32 s15, s20, s15
	v_lshl_add_u64 v[18:19], s[14:15], 0, v[0:1]
	s_or_b32 s14, s35, 1
	s_mul_hi_i32 s15, s14, 0x6000
	s_mulk_i32 s14, 0x6000
	s_add_u32 s14, s19, s14
	s_addc_u32 s15, s20, s15
	v_lshl_add_u64 v[34:35], s[14:15], 0, v[0:1]
	s_or_b32 s14, s35, 2
	s_mul_hi_i32 s15, s14, 0x6000
	s_mulk_i32 s14, 0x6000
	s_movk_i32 s24, 0x2000
	s_add_u32 s14, s19, s14
	v_lshl_add_u64 v[30:31], v[18:19], 0, s[78:79]
	v_add_co_u32_e32 v18, vcc, s24, v18
	s_addc_u32 s15, s20, s15
	s_nop 0
	v_addc_co_u32_e32 v19, vcc, 0, v19, vcc
	v_lshl_add_u64 v[50:51], s[14:15], 0, v[0:1]
	s_or_b32 s14, s35, 3
	v_lshl_add_u64 v[46:47], v[34:35], 0, s[78:79]
	v_add_co_u32_e32 v34, vcc, s24, v34
	s_mul_hi_i32 s15, s14, 0x6000
	s_mulk_i32 s14, 0x6000
	v_addc_co_u32_e32 v35, vcc, 0, v35, vcc
	s_add_u32 s14, s19, s14
	v_lshl_add_u64 v[62:63], v[50:51], 0, s[78:79]
	v_add_co_u32_e32 v50, vcc, s24, v50
	s_addc_u32 s15, s20, s15
	s_nop 0
	v_addc_co_u32_e32 v51, vcc, 0, v51, vcc
	v_lshl_add_u64 v[66:67], s[14:15], 0, v[0:1]
	v_lshl_add_u64 v[78:79], v[66:67], 0, s[78:79]
	v_add_co_u32_e32 v66, vcc, s24, v66
	s_nop 0
	s_nop 0
	v_addc_co_u32_e32 v67, vcc, 0, v67, vcc
	s_nop 0
	s_nop 0
	s_nop 0
	s_nop 0
	s_nop 0
	s_nop 0
	s_nop 0
	s_nop 0
	global_load_dwordx4 v[220:223], v224, s[98:99]
	s_waitcnt vmcnt(0)
	ds_write_b128 v225, v[220:223]
	s_waitcnt lgkmcnt(0)
	ds_read_b128 v[18:21], v226
	ds_read_b128 v[30:33], v226 offset:16
	ds_read_b128 v[26:29], v226 offset:32
	ds_read_b128 v[22:25], v226 offset:48
	ds_read_b128 v[34:37], v226 offset:256
	ds_read_b128 v[46:49], v226 offset:272
	ds_read_b128 v[42:45], v226 offset:288
	ds_read_b128 v[38:41], v226 offset:304
	ds_read_b128 v[50:53], v226 offset:512
	ds_read_b128 v[62:65], v226 offset:528
	ds_read_b128 v[58:61], v226 offset:544
	ds_read_b128 v[54:57], v226 offset:560
	ds_read_b128 v[66:69], v226 offset:768
	ds_read_b128 v[78:81], v226 offset:784
	ds_read_b128 v[74:77], v226 offset:800
	ds_read_b128 v[70:73], v226 offset:816
	s_waitcnt lgkmcnt(0)
	v_lshl_add_u64 v[184:185], s[50:51], 0, v[82:83]
	v_add_u32_e32 v82, s44, v213
	v_ashrrev_i32_e32 v83, 31, v82
	v_lshlrev_b64 v[82:83], 9, v[82:83]
	s_mul_hi_i32 s35, s28, 40
	s_mul_i32 s36, s28, 40
	s_mul_hi_i32 s37, s34, 40
	s_mul_i32 s38, s34, 40
	s_mul_hi_i32 s39, s31, 40
	s_mul_i32 s66, s31, 40
	s_mul_hi_i32 s67, s29, 40
	s_mul_i32 s72, s29, 40
	s_mov_b32 s73, 0
	v_lshl_add_u64 v[186:187], s[50:51], 0, v[82:83]
	s_mov_b64 s[62:63], s[52:53]
	s_branch .LBB0_286

; __device__ __forceinline__ void moba_select_phase(Frame& F) {
;     ...
;             if (h + 2 < MOBA_H) MS_LOAD(kmA, qA, h + 2);
.LBB0_302:
	s_or_b64 exec, exec, s[14:15]
	v_lshl_add_u64 v[210:211], s[60:61], 0, v[164:165]
	v_add_co_u32_e32 v100, vcc, 0x3c902000, v210
	v_lshl_add_u64 v[208:209], s[58:59], 0, v[164:165]
	s_nop 0
	v_addc_co_u32_e32 v101, vcc, 0, v211, vcc
	v_lshl_add_u64 v[98:99], v[210:211], 0, s[4:5]
	v_add_co_u32_e32 v100, vcc, 0x3c902000, v208
	v_lshl_add_u64 v[206:207], s[56:57], 0, v[164:165]
	s_nop 0
	v_addc_co_u32_e32 v101, vcc, 0, v209, vcc
	v_lshl_add_u64 v[98:99], v[208:209], 0, s[4:5]
	v_add_co_u32_e32 v100, vcc, 0x3c902000, v206
	v_lshl_add_u64 v[98:99], v[206:207], 0, s[4:5]
	s_nop 0
	v_addc_co_u32_e32 v101, vcc, 0, v207, vcc
	v_lshl_add_u64 v[204:205], s[54:55], 0, v[164:165]
	v_add_co_u32_e32 v98, vcc, 0x3c902000, v204
	v_lshl_add_u64 v[110:111], v[204:205], 0, s[4:5]
	s_nop 0
	v_addc_co_u32_e32 v99, vcc, 0, v205, vcc
	s_nop 0
	s_nop 0
	s_lshl_b32 s32, s73, 8
	s_add_u32 s90, s98, s32
	s_addc_u32 s91, s99, 0
	global_load_dwordx4 v[220:223], v224, s[90:91] offset:256
	s_waitcnt vmcnt(0)
	ds_write_b128 v225, v[220:223]
	s_waitcnt lgkmcnt(0)
	ds_read_b128 v[154:157], v226
	ds_read_b128 v[158:161], v226 offset:16
	ds_read_b128 v[150:153], v226 offset:32
	ds_read_b128 v[146:149], v226 offset:48
	ds_read_b128 v[138:141], v226 offset:256
	ds_read_b128 v[142:145], v226 offset:272
	ds_read_b128 v[134:137], v226 offset:288
	ds_read_b128 v[130:133], v226 offset:304
	ds_read_b128 v[122:125], v226 offset:512
	ds_read_b128 v[126:129], v226 offset:528
	ds_read_b128 v[118:121], v226 offset:544
	ds_read_b128 v[114:117], v226 offset:560
	ds_read_b128 v[106:109], v226 offset:768
	ds_read_b128 v[110:113], v226 offset:784
	ds_read_b128 v[102:105], v226 offset:800
	ds_read_b128 v[98:101], v226 offset:816
	s_waitcnt lgkmcnt(0)
	s_waitcnt vmcnt(0)
	v_and_b32_e32 v217, 0xffff0000, v18
	v_and_b32_e32 v216, 0xffff0000, v30
	v_lshlrev_b32_e32 v215, 16, v18
	v_lshlrev_b32_e32 v214, 16, v30
	v_pk_mul_f32 v[216:217], v[2:3], v[216:217]
	s_nop 0
	v_pk_fma_f32 v[214:215], v[170:171], v[214:215], v[216:217]
	v_lshlrev_b32_e32 v217, 16, v19
	v_lshlrev_b32_e32 v216, 16, v31
	v_pk_fma_f32 v[214:215], v[172:173], v[216:217], v[214:215]
	v_and_b32_e32 v217, 0xffff0000, v19
	v_and_b32_e32 v216, 0xffff0000, v31
	v_pk_fma_f32 v[214:215], v[4:5], v[216:217], v[214:215]
	v_lshlrev_b32_e32 v217, 16, v20
	v_lshlrev_b32_e32 v216, 16, v32
	v_pk_fma_f32 v[214:215], v[168:169], v[216:217], v[214:215]
	v_and_b32_e32 v217, 0xffff0000, v20
	v_and_b32_e32 v216, 0xffff0000, v32
	v_pk_fma_f32 v[214:215], v[6:7], v[216:217], v[214:215]
	v_lshlrev_b32_e32 v217, 16, v21
	v_lshlrev_b32_e32 v216, 16, v33
	v_pk_fma_f32 v[214:215], v[174:175], v[216:217], v[214:215]
	v_and_b32_e32 v217, 0xffff0000, v21
	v_and_b32_e32 v216, 0xffff0000, v33
	v_pk_fma_f32 v[214:215], v[8:9], v[216:217], v[214:215]
	v_and_b32_e32 v217, 0xffff0000, v26
	v_add_f32_e32 v215, 0, v215
	v_and_b32_e32 v216, 0xffff0000, v22
	v_add_f32_e32 v218, v214, v215
	v_lshlrev_b32_e32 v215, 16, v26
	v_lshlrev_b32_e32 v214, 16, v22
	v_pk_mul_f32 v[216:217], v[10:11], v[216:217]
	s_nop 0
	v_pk_fma_f32 v[214:215], v[178:179], v[214:215], v[216:217]
	v_lshlrev_b32_e32 v217, 16, v27
	v_lshlrev_b32_e32 v216, 16, v23
	v_pk_fma_f32 v[214:215], v[180:181], v[216:217], v[214:215]
	v_and_b32_e32 v217, 0xffff0000, v27
	v_and_b32_e32 v216, 0xffff0000, v23
	v_pk_fma_f32 v[214:215], v[12:13], v[216:217], v[214:215]
	v_lshlrev_b32_e32 v217, 16, v28
	v_lshlrev_b32_e32 v216, 16, v24
	v_pk_fma_f32 v[214:215], v[176:177], v[216:217], v[214:215]
	v_and_b32_e32 v217, 0xffff0000, v28
	v_and_b32_e32 v216, 0xffff0000, v24
	v_pk_fma_f32 v[214:215], v[14:15], v[216:217], v[214:215]
	v_lshlrev_b32_e32 v217, 16, v29
	v_lshlrev_b32_e32 v216, 16, v25
	v_pk_fma_f32 v[214:215], v[182:183], v[216:217], v[214:215]
	v_and_b32_e32 v217, 0xffff0000, v29
	v_and_b32_e32 v216, 0xffff0000, v25
	v_pk_fma_f32 v[214:215], v[16:17], v[216:217], v[214:215]
	s_nop 0
	v_add_f32_e32 v215, v215, v218
	v_add_f32_e32 v214, v214, v215
	s_nop 1
	v_add_f32_dpp v214, v214, v214 quad_perm:[1,0,3,2] row_mask:0xf bank_mask:0xf bound_ctrl:1
	s_nop 1
	v_add_f32_dpp v214, v214, v214 quad_perm:[2,3,0,1] row_mask:0xf bank_mask:0xf bound_ctrl:1
	v_ashrrev_i32_e32 v215, 31, v214
	v_bitop3_b32 v215, v215, v214, s1 bitop3:0x6c
	v_cndmask_b32_e64 v214, v246, v215, s[42:43]
	s_nop 1
	v_max_i32_dpp v214, v214, v214 row_half_mirror row_mask:0xf bank_mask:0xf bound_ctrl:1
	s_nop 1
	v_max_i32_dpp v214, v214, v214 row_mirror row_mask:0xf bank_mask:0xf bound_ctrl:1
	v_mov_b32_e32 v216, v214
	s_nop 1
	v_permlane16_swap_b32_e32 v214, v216
	v_max_i32_e32 v214, v214, v216
	v_mov_b32_e32 v216, v214
	s_nop 1
	v_permlane32_swap_b32_e32 v214, v216
	v_max_i32_e32 v214, v214, v216
	v_cmp_eq_u32_e32 vcc, v215, v214
	s_and_b64 s[14:15], s[42:43], vcc
	v_cndmask_b32_e64 v214, 0, 1, s[14:15]
	v_cmp_ne_u32_e64 s[44:45], 0, v214
	s_cmp_eq_u64 s[44:45], 0
	s_ff1_i32_b64 s14, s[44:45]
	s_cselect_b64 vcc, -1, 0
	s_lshr_b32 s24, s14, 2
	v_cmp_ne_u32_e64 s[44:45], s24, v212
	s_and_b64 s[14:15], s[42:43], s[44:45]
	v_cndmask_b32_e64 v214, 0, 1, s[42:43]
	v_cndmask_b32_e64 v216, 0, 1, s[14:15]
	v_cndmask_b32_e32 v216, v216, v214, vcc
	v_and_b32_e32 v217, 1, v216
	v_cmp_eq_u32_e64 s[46:47], 1, v217
	s_nop 1
	v_cndmask_b32_e64 v217, v246, v215, s[46:47]
	s_nop 1
	v_max_i32_dpp v217, v217, v217 row_half_mirror row_mask:0xf bank_mask:0xf bound_ctrl:1
	s_nop 1
	v_max_i32_dpp v217, v217, v217 row_mirror row_mask:0xf bank_mask:0xf bound_ctrl:1
	v_mov_b32_e32 v218, v217
	s_nop 1
	v_permlane16_swap_b32_e32 v217, v218
	v_max_i32_e32 v217, v217, v218
	v_mov_b32_e32 v218, v217
	s_nop 1
	v_permlane32_swap_b32_e32 v217, v218
	v_max_i32_e32 v217, v217, v218
	v_cmp_eq_u32_e64 s[44:45], v215, v217
	s_and_b64 s[14:15], s[46:47], s[44:45]
	v_cndmask_b32_e64 v217, 0, 1, s[14:15]
	v_cmp_ne_u32_e64 s[48:49], 0, v217
	s_cmp_eq_u64 s[48:49], 0
	s_ff1_i32_b64 s14, s[48:49]
	s_cselect_b64 s[44:45], -1, 0
	s_lshr_b32 s64, s14, 2
	v_cmp_ne_u32_e64 s[48:49], s64, v212
	s_and_b64 s[14:15], s[46:47], s[48:49]
	v_cndmask_b32_e64 v217, 0, 1, s[14:15]
	v_cndmask_b32_e64 v216, v217, v216, s[44:45]
	v_and_b32_e32 v216, 1, v216
	v_cmp_eq_u32_e64 s[46:47], 1, v216
	s_nop 1
	v_cndmask_b32_e64 v216, v246, v215, s[46:47]
	s_nop 1
	v_max_i32_dpp v216, v216, v216 row_half_mirror row_mask:0xf bank_mask:0xf bound_ctrl:1
	s_nop 1
	v_max_i32_dpp v216, v216, v216 row_mirror row_mask:0xf bank_mask:0xf bound_ctrl:1
	v_mov_b32_e32 v217, v216
	s_nop 1
	v_permlane16_swap_b32_e32 v216, v217
	v_max_i32_e32 v216, v216, v217
	v_mov_b32_e32 v217, v216
	s_nop 1
	v_permlane32_swap_b32_e32 v216, v217
	v_max_i32_e32 v216, v216, v217
	v_cmp_eq_u32_e64 s[48:49], v215, v216
	s_and_b64 s[14:15], s[46:47], s[48:49]
	v_cndmask_b32_e64 v215, 0, 1, s[14:15]
	v_cmp_ne_u32_e64 s[46:47], 0, v215
	s_and_saveexec_b64 s[14:15], s[40:41]
	s_cbranch_execz .LBB0_304
	s_ff1_i32_b64 s48, s[46:47]
	s_lshr_b32 s48, s48, 2
	s_lshl_b32 s48, 1, s48
	s_cmp_lg_u64 s[46:47], 0
	s_cselect_b32 s46, s48, 0
	s_lshl_b32 s47, 1, s64
	s_and_b64 s[44:45], s[44:45], exec
	s_cselect_b32 s47, 0, s47
	s_lshl_b32 s24, 1, s24
	s_and_b64 s[44:45], vcc, exec
	s_cselect_b32 s24, 0, s24
	s_or_b32 s24, s47, s24
	s_or_b32 s24, s24, s46
	s_add_u32 s44, s62, s36
	s_addc_u32 s45, s63, s35
	v_mov_b32_e32 v215, s44
	v_add_co_u32_e32 v216, vcc, 0x72700000, v215
	v_mov_b32_e32 v215, s45
	s_nop 0
	v_addc_co_u32_e32 v217, vcc, 0, v215, vcc
	v_mov_b32_e32 v215, s24
	flat_store_dword v[216:217], v215

; __device__ __forceinline__ void moba_select_phase(Frame& F) {
;     ...
;             if (h + 2 < MOBA_H) MS_LOAD(kmA, qA, h + 2);
.LBB0_327:
	s_or_b64 exec, exec, s[14:15]
	v_add_co_u32_e32 v18, vcc, 0x3c902000, v210
	v_lshl_add_u64 v[30:31], v[210:211], 0, s[6:7]
	s_nop 0
	v_addc_co_u32_e32 v19, vcc, 0, v211, vcc
	v_add_co_u32_e32 v34, vcc, s0, v208
	v_lshl_add_u64 v[46:47], v[208:209], 0, s[6:7]
	s_nop 0
	v_addc_co_u32_e32 v35, vcc, 0, v209, vcc
	v_add_co_u32_e32 v50, vcc, s0, v206
	v_lshl_add_u64 v[62:63], v[206:207], 0, s[6:7]
	s_nop 0
	v_addc_co_u32_e32 v51, vcc, 0, v207, vcc
	v_add_co_u32_e32 v66, vcc, s0, v204
	v_lshl_add_u64 v[78:79], v[204:205], 0, s[6:7]
	s_nop 0
	v_addc_co_u32_e32 v67, vcc, 0, v205, vcc
	s_nop 0
	s_nop 0
	s_nop 0
	s_nop 0
	s_nop 0
	s_nop 0
	s_nop 0
	s_nop 0
	s_nop 0
	s_nop 0
	s_nop 0
	s_lshl_b32 s32, s73, 8
	s_add_u32 s90, s98, s32
	s_addc_u32 s91, s99, 0
	global_load_dwordx4 v[220:223], v224, s[90:91] offset:512
	s_waitcnt vmcnt(0)
	ds_write_b128 v225, v[220:223]
	s_waitcnt lgkmcnt(0)
	ds_read_b128 v[18:21], v226
	ds_read_b128 v[30:33], v226 offset:16
	ds_read_b128 v[26:29], v226 offset:32
	ds_read_b128 v[22:25], v226 offset:48
	ds_read_b128 v[34:37], v226 offset:256
	ds_read_b128 v[46:49], v226 offset:272
	ds_read_b128 v[42:45], v226 offset:288
	ds_read_b128 v[38:41], v226 offset:304
	ds_read_b128 v[50:53], v226 offset:512
	ds_read_b128 v[62:65], v226 offset:528
	ds_read_b128 v[58:61], v226 offset:544
	ds_read_b128 v[54:57], v226 offset:560
	ds_read_b128 v[66:69], v226 offset:768
	ds_read_b128 v[78:81], v226 offset:784
	ds_read_b128 v[74:77], v226 offset:800
	ds_read_b128 v[70:73], v226 offset:816
	s_waitcnt lgkmcnt(0)
